# lever 4: one static s_setprio 1 for waves 4-7 across the sparse-attention block (reset to 0 at block end)
# baseline (speedup 1.0000x reference)
; DI void nsa_block(const P& p, int layer, int T, float* ldsf) {
;     ...
;   const int tid = tid_, lane = tid & 63, wid = tid >> 6, r = lane & 31, h = lane >> 5;
;   const int hd = wid & 3, half = wid >> 2, t = T * 32 + r;
;   const bf16_t* proj = (const bf16_t*)(ws + OFF_PROJ);
;   const bf16_t* qn = (const bf16_t*)(ws + OFF_QN);
;   bf16_t* mix = (bf16_t*)(ws + OFF_MIX);
;   __syncthreads();
;   bf16x8 qf[8];
;   loadq(qf, qn + (long)t * 512 + hd * 128 + 8 * h);
;   const bf16_t* grow0 = proj + (long)t * NPJ + 6912 + hd * 3;
;   const bf16_t gr0 = grow0[0], gr1 = grow0[1], gr2 = grow0[2];
;   f32x16 o[4];
;     ...
;   for (int rep = 0; rep < 4; ++rep) {
;     float m = 0.f, l = 0.f; zero4(o);
;     nsa_pass<1>(lds, (const bf16_t*)(ws + OFF_KCMP), (const bf16_t*)(ws + OFF_VCMPT), 512, 0, (2 * T) >> 6, qf, o, m, l, 0.f, T, t, r, h, hd, half, tid, 0, 0, 0, 0);
;     nsa_merge(lds, o, m, l, true, hd, half, lane);
;   }
;     ...
;   for (int i = tid; i < (65536 + 8192) / 4; i += 512) ldsf[i] = 0.f;
; DI void phase_l6(const P& p, int layer, float* ldsf) {
;     ...
;   for (int id = bid_; id < 256; id += gridDim.x) nsa_block(p, layer, 255 - id, ldsf);
.LBB0_95:
	s_or_b64 exec, exec, s[0:1]
	s_setprio 0
	s_barrier
	s_load_dword s0, s[28:29], 0x0
	s_waitcnt lgkmcnt(0)
	s_add_i32 s20, s0, s20
	s_cmpk_gt_i32 s20, 0xff
	s_cbranch_scc1 .LBB0_85
.LBB0_96:
	s_sub_i32 s22, 0xff, s20
	v_mov_b32_e32 v170, v204
	s_lshl_b32 s21, s22, 5
	v_and_b32_e32 v191, 31, v170
	v_ashrrev_i32_e32 v171, 6, v170
	s_nop 0
	v_readfirstlane_b32 s0, v171
	s_cmp_lt_u32 s0, 4
	s_cbranch_scc1 .Lnsa_prio_done
	s_setprio 1
.Lnsa_prio_done:
	v_or_b32_e32 v0, s21, v191
	v_and_b32_e32 v173, 3, v171
	s_waitcnt vmcnt(0)
	v_lshlrev_b64 v[2:3], 10, v[0:1]
	v_bfe_u32 v147, v170, 5, 1
	v_lshl_add_u64 v[2:3], s[30:31], 0, v[2:3]
	v_lshlrev_b32_e32 v4, 8, v173
	v_mov_b32_e32 v5, v1
	v_lshl_add_u64 v[2:3], v[2:3], 0, v[4:5]
	v_lshlrev_b32_e32 v150, 4, v147
	v_mov_b32_e32 v151, v1
	s_mov_b32 s0, s77
	v_lshl_add_u64 v[2:3], v[2:3], 0, v[150:151]
	s_barrier
	global_load_dwordx4 v[82:85], v[2:3], off
	global_load_dwordx4 v[86:89], v[2:3], off offset:32
	global_load_dwordx4 v[90:93], v[2:3], off offset:64
	global_load_dwordx4 v[94:97], v[2:3], off offset:96
	global_load_dwordx4 v[98:101], v[2:3], off offset:128
	global_load_dwordx4 v[102:105], v[2:3], off offset:160
	global_load_dwordx4 v[106:109], v[2:3], off offset:192
	global_load_dwordx4 v[110:113], v[2:3], off offset:224
	v_mov_b64_e32 v[2:3], s[46:47]
	v_mul_u32_u24_e32 v4, 3, v173
	v_mad_u64_u32 v[2:3], s[0:1], v0, s44, v[2:3]
	v_lshlrev_b32_e32 v4, 1, v4
	v_lshl_add_u64 v[2:3], v[2:3], 0, v[4:5]
	s_mov_b64 s[0:1], 0x6003600
	v_lshl_add_u64 v[4:5], v[2:3], 0, s[0:1]
	v_add_co_u32_e32 v2, vcc, 0x6003000, v2
	s_movk_i32 s0, 0x4800
	s_nop 0
	v_addc_co_u32_e32 v3, vcc, 0, v3, vcc
	global_load_dword v197, v[2:3], off offset:1536
	global_load_ushort v177, v[4:5], off offset:4
	v_cmp_gt_i32_e32 vcc, s0, v170
	v_lshl_add_u32 v172, v170, 2, 0
	s_and_saveexec_b64 s[0:1], vcc
	s_cbranch_execz .LBB0_99
	v_add_u32_e32 v2, 0xfffffe00, v170
	s_mov_b64 s[2:3], 0
	v_mov_b32_e32 v3, v172
